# P2 end-of-unit waits vmcnt(12..9) instead of (11..8): every wave issues the lse store, so the 9 younger stores no longer force the first output store to complete before the next unit commits
# baseline (speedup 1.0000x reference)
; __global__ void __launch_bounds__(NTHREADS, 2) fwd_megakernel(Args args) {
;     ...
;         for (int uid = u0; uid < u1; ++uid) {
;             const AttnUnit u = attn_decode(uid);
;             attn_commit(R, u.n, true, lds);
;             bf16x8 qf[4];
; #pragma unroll
;             for (int s4 = 0; s4 < 4; ++s4) qf[s4] = R.qf[s4];
;             asm volatile("s_waitcnt lgkmcnt(0)" ::: "memory"); __builtin_amdgcn_s_barrier(); asm volatile("" ::: "memory");
;             if (uid + 1 < u1) { const AttnUnit un = attn_decode(uid + 1); attn_issue(R, un, un.n, true, PROJ, BIAS2); }
.LBB0_146:
	s_or_b64 exec, exec, s[60:61]
	s_waitcnt lgkmcnt(0)
	s_barrier
	s_waitcnt vmcnt(12)
	v_mov_b64_e32 v[62:63], v[34:35]
	s_waitcnt vmcnt(11)
	v_mov_b64_e32 v[58:59], v[38:39]
	s_waitcnt vmcnt(10)
	v_mov_b64_e32 v[54:55], v[42:43]
	s_waitcnt vmcnt(9)
	v_mov_b64_e32 v[50:51], v[46:47]
	s_and_b64 vcc, exec, s[58:59]
	v_mov_b64_e32 v[60:61], v[32:33]
	v_mov_b64_e32 v[56:57], v[36:37]
	v_mov_b64_e32 v[52:53], v[40:41]
	v_mov_b64_e32 v[48:49], v[44:45]
	s_mov_b32 s11, s75
	s_cbranch_vccnz .LBB0_153
